# P4->P5 and P6->P7 seams synchronise only the 4 workgroups sharing a panel pair (same-XCC checked at run time, else original group barrier); P6 remapped quad-local
# speedup vs baseline: 1.0121x; 1.0106x over previous
; #define LAS __attribute__((address_space(3)))
; __device__ __forceinline__ XcdBarrier xcd_barrier_post(unsigned* bar, volatile LAS unsigned* st, unsigned gsize) {
;     XcdBarrier b; b.bar = bar; b.x = xb_xcc_id(); b.st = st; b.gsize = gsize;
;     if (threadIdx.x == 0) (void)xb_add(&bar[XB_XCNT(b.x)], 1u);
;     return b;
; __global__ void __launch_bounds__(NWAVES * 64, 2) fwd(Args a) {
;     extern __shared__ __attribute__((aligned(16))) unsigned char lds_raw[];
;     LAS unsigned char* lds = (LAS unsigned char*)lds_raw;
;     volatile LAS unsigned* MISC = (volatile LAS unsigned*)(lds + MISC_OFF);
;     const int wave = __builtin_amdgcn_readfirstlane((int)threadIdx.x >> 6);
;     ...
;     const int G = gridDim.x; const int bx = blockIdx.x; const int vcu = (bx % 8) * (G / 8) + bx / 8;
;     const int gw = vcu * NWAVES + wave, NGW = G * NWAVES;
;     const int grp = (bx & 7) >> 1, xh = bx & 1, gk = bx >> 3, cph = G >> 3, gsz = G >> 2, pm0 = GPANELS * grp;
;     unsigned char* ws = a.ws;
;     unsigned* ctl = (unsigned*)(ws + WS_CTL);
;     float* macc = (float*)(ws + OFF_MOD); float* c2acc = (float*)(ws + OFF_C2); float* rss2 = (float*)(ws + OFF_RSS2); float* hss = (float*)(ws + OFF_HSS);
;     bf16* WinT = (bf16*)(ws + WS_WIN); bf16* WoT = (bf16*)(ws + WS_WOUT); bf16* WupT = (bf16*)(ws + WS_WUP); bf16* WdT = (bf16*)(ws + WS_WDN);
;     float* convp = (float*)(ws + WS_SMALL); float* cbp = convp + 3 * FF2;
;     float* g1t = (float*)(ws + WS_SMALL + 131072); float* G2t = g1t + NBATCH * D; float* g2t = G2t + NBATCH * D; float* iG2t = g2t + NBATCH * D;
;     float* EDGE = (float*)(ws + WS_EDGE);
;     unsigned char* slice = ws + WS_SLICE0 + (size_t)grp * WS_SLICE;
;     bf16* H1g = (bf16*)(slice + SL_H1); bf16* PROJg = (bf16*)(slice + SL_PROJ); bf16* CATg = (bf16*)(slice + SL_CAT); unsigned short* X1g = (unsigned short*)(slice + SL_X1); bf16* XG2g = (bf16*)(slice + SL_XG2); bf16* ACTg = (bf16*)(slice + SL_ACT);
;     const float* b_ada = a.in[I_BADA];
;     for (int u = threadIdx.x; u < (LDS_BYTES - LDSCTL_OFF) / 4; u += NWAVES * 64) ((LAS unsigned*)(lds + LDSCTL_OFF))[u] = 0u;
;     __syncthreads();
;     XcdBarrier bar = xcd_barrier_post(ctl + CW_BAR, MISC + 8, (unsigned)G);
;     XcdBarrier barg = xcd_barrier_post(ctl + CW_GBAR + grp * XCD_BAR_WORDS, MISC + 12, (unsigned)gsz);
_Z3fwd4Args:
	s_load_dwordx8 s[4:11], s[0:1], 0x80
	s_load_dwordx2 s[14:15], s[0:1], 0xa0
	s_load_dword s83, s[0:1], 0xb8
	s_mov_b32 s101, s2
	v_lshl_add_u32 v1, v0, 2, 0
	v_add_u32_e32 v1, 0x26000, v1
	v_mov_b32_e32 v2, 0
	s_waitcnt lgkmcnt(0)
	v_writelane_b32 v250, s4, 0
	ds_write2st64_b32 v1, v2, v2 offset1:8
	v_or_b32_e32 v1, 0x400, v0
	v_writelane_b32 v250, s5, 1
	v_writelane_b32 v250, s6, 2
	v_writelane_b32 v250, s7, 3
	v_writelane_b32 v250, s8, 4
	v_writelane_b32 v250, s9, 5
	v_writelane_b32 v250, s10, 6
	v_writelane_b32 v250, s11, 7
	v_readfirstlane_b32 s11, v0
	s_mov_b64 s[4:5], -1
	s_and_saveexec_b64 s[6:7], s[4:5]
	v_lshl_add_u32 v3, v1, 2, 0
	v_add_u32_e32 v3, 0x26000, v3
	ds_write_b32 v3, v2
	s_or_b64 exec, exec, s[6:7]
	s_and_saveexec_b64 s[6:7], s[4:5]
	s_add_i32 s3, 0, 0x26000
	v_lshl_add_u32 v1, v1, 2, s3
	v_mov_b32_e32 v2, 0
	ds_write_b32 v1, v2 offset:2048
	s_or_b64 exec, exec, s[6:7]
	s_waitcnt lgkmcnt(0)
	s_barrier
	s_add_u32 s16, s14, 0x4000
	s_getreg_b32 s3, hwreg(HW_REG_XCC_ID, 0, 4)
	s_addc_u32 s17, s15, 0
	s_and_b32 s3, s3, 15
	v_cmp_eq_u32_e64 s[12:13], 0, v0
	s_and_saveexec_b64 s[4:5], s[12:13]
	s_cbranch_execz .LBB0_7
	s_mov_b64 s[6:7], exec
	v_mbcnt_lo_u32_b32 v1, s6, 0
	v_mbcnt_hi_u32_b32 v1, s7, v1
	v_cmp_eq_u32_e32 vcc, 0, v1
	s_and_b64 s[8:9], exec, vcc
	s_mov_b64 exec, s[8:9]
	s_cbranch_execz .LBB0_7
	s_lshl_b32 s8, s3, 8
	s_bcnt1_i32_b64 s6, s[6:7]
	v_mov_b32_e32 v1, s8
	v_mov_b32_e32 v2, s6
	global_atomic_add v1, v2, s[16:17] offset:1024

; #define LAS __attribute__((address_space(3)))
; __global__ void __launch_bounds__(NWAVES * 64, 2) fwd(Args a) {
;     ...
;     const int G = gridDim.x; const int bx = blockIdx.x; const int vcu = (bx % 8) * (G / 8) + bx / 8;
;     const int gw = vcu * NWAVES + wave, NGW = G * NWAVES;
;     const int grp = (bx & 7) >> 1, xh = bx & 1, gk = bx >> 3, cph = G >> 3, gsz = G >> 2, pm0 = GPANELS * grp;
;     unsigned char* ws = a.ws;
;     unsigned* ctl = (unsigned*)(ws + WS_CTL);
;     float* macc = (float*)(ws + OFF_MOD); float* c2acc = (float*)(ws + OFF_C2); float* rss2 = (float*)(ws + OFF_RSS2); float* hss = (float*)(ws + OFF_HSS);
;     bf16* WinT = (bf16*)(ws + WS_WIN); bf16* WoT = (bf16*)(ws + WS_WOUT); bf16* WupT = (bf16*)(ws + WS_WUP); bf16* WdT = (bf16*)(ws + WS_WDN);
;     float* convp = (float*)(ws + WS_SMALL); float* cbp = convp + 3 * FF2;
;     float* g1t = (float*)(ws + WS_SMALL + 131072); float* G2t = g1t + NBATCH * D; float* g2t = G2t + NBATCH * D; float* iG2t = g2t + NBATCH * D;
;     float* EDGE = (float*)(ws + WS_EDGE);
;     unsigned char* slice = ws + WS_SLICE0 + (size_t)grp * WS_SLICE;
;     bf16* H1g = (bf16*)(slice + SL_H1); bf16* PROJg = (bf16*)(slice + SL_PROJ); bf16* CATg = (bf16*)(slice + SL_CAT); unsigned short* X1g = (unsigned short*)(slice + SL_X1); bf16* XG2g = (bf16*)(slice + SL_XG2); bf16* ACTg = (bf16*)(slice + SL_ACT);
;     const float* b_ada = a.in[I_BADA];
;     for (int u = threadIdx.x; u < (LDS_BYTES - LDSCTL_OFF) / 4; u += NWAVES * 64) ((LAS unsigned*)(lds + LDSCTL_OFF))[u] = 0u;
;     __syncthreads();
;     XcdBarrier bar = xcd_barrier_post(ctl + CW_BAR, MISC + 8, (unsigned)G);
;     XcdBarrier barg = xcd_barrier_post(ctl + CW_GBAR + grp * XCD_BAR_WORDS, MISC + 12, (unsigned)gsz);
;     ...
;     for (int rep = 0; rep <= PROBE_REPS(0); ++rep) { const float asc = rep ? 0.f : 1.f; (void)asc;
;     if (IN(0)) {
;         LANE_SETUP();
;         LAS float* scr = (LAS float*)(lds + RING_OFF + wave * 16384);
;         for (int it = gw; it < 16 * 96; it += NGW) {
;             const int kc = it / 96, nc = it % 96, k = 64 * kc + lane;
;             const float* cp = a.in[I_CP]; const float* cs = a.in[I_CS];
;             gemv10_item(a.in[I_WADA], MODW, 64 * kc, 64 * nc + lane, scr, macc, MODW, 64 * nc + lane, asc, [=](LAS float* sb) {
; #pragma unroll
.LBB0_10:
	v_writelane_b32 v250, s10, 13
	s_or_b64 exec, exec, s[4:5]
	s_and_saveexec_b64 s[4:5], s[12:13]
	s_cbranch_execz .Lqx_post_done
	s_and_b32 s6, s2, 7
	s_lshl_b32 s6, s6, 3
	s_bfe_u32 s7, s2, 0x30003
	s_or_b32 s6, s6, s7
	s_lshl_b32 s6, s6, 2
	s_add_i32 s6, s6, 0x18000
	v_mov_b32_e32 v1, s6
	s_lshl_b32 s7, 1, s10
	v_mov_b32_e32 v2, s7
	global_atomic_or v1, v2, s[14:15]
.Lqx_post_done:
	s_or_b64 exec, exec, s[4:5]
	s_lshl_b32 s76, s83, 3
	s_add_u32 s72, s14, 0x20000
	v_writelane_b32 v250, s14, 14
	s_addc_u32 s73, s15, 0
	s_ashr_i32 s4, s2, 31
	s_lshr_b32 s4, s4, 29
	s_ashr_i32 s6, s83, 31
	v_writelane_b32 v250, s15, 15
	s_add_i32 s4, s2, s4
	s_lshr_b32 s6, s6, 29
	v_writelane_b32 v250, s11, 16
	s_lshr_b32 s5, s4, 3
	s_and_b32 s4, s4, -8
	s_add_i32 s6, s83, s6
	v_writelane_b32 v250, s4, 17
	s_sub_i32 s4, s2, s4
	s_ashr_i32 s90, s6, 3
	s_load_dwordx16 s[36:51], s[0:1], 0x0
	s_mul_i32 s4, s90, s4
	s_lshr_b32 s88, s11, 6
	v_writelane_b32 v250, s4, 18
	s_add_i32 s4, s4, s5
	s_lshl_b32 s77, s4, 3
	s_lshl_b32 s4, s88, 14
	s_add_i32 s77, s77, s88
	s_add_i32 s78, s4, 0
	s_cmpk_lt_i32 s77, 0x600
	v_mov_b32_e32 v1, v0
	s_cbranch_scc0 .LBB0_13
	v_and_b32_e32 v1, 63, v1
	v_mul_u32_u24_e32 v2, 48, v1
	v_lshl_or_b32 v156, s77, 6, v1
	s_lshl_b32 s24, s76, 6
	s_movk_i32 s25, 0x6000
	v_mov_b32_e32 v157, 0x6000
	v_add_u32_e32 v158, s78, v2
	v_mov_b32_e32 v159, s78
	s_mov_b32 s26, s77

; __global__ void __launch_bounds__(NWAVES * 64, 2) fwd(Args a) {
;     ...
;     XcdBarrier bar = xcd_barrier_post(ctl + CW_BAR, MISC + 8, (unsigned)G);
;     XcdBarrier barg = xcd_barrier_post(ctl + CW_GBAR + grp * XCD_BAR_WORDS, MISC + 12, (unsigned)gsz);
.LBB0_65:
	s_or_b64 exec, exec, s[4:5]
	s_and_saveexec_b64 s[4:5], s[80:81]
	s_cbranch_execz .Lqx_chk_done
	s_and_b32 s6, s101, 7
	s_lshl_b32 s6, s6, 3
	s_bfe_u32 s7, s101, 0x30003
	s_or_b32 s6, s6, s7
	s_lshl_b32 s6, s6, 2
	s_add_i32 s6, s6, 0x18000
	v_mov_b32_e32 v1, s6
	global_load_dword v2, v1, s[60:61] sc1
	s_waitcnt vmcnt(0)
	v_add_u32_e32 v3, -1, v2
	v_and_b32_e32 v3, v3, v2
	v_cmp_ne_u32_e32 vcc, 0, v3
	s_cbranch_vccz .Lqx_chk_done
	v_mov_b32_e32 v1, 0x18800
	v_mov_b32_e32 v2, 1
	global_atomic_add v1, v2, s[60:61]

; template <class Epi, class Sched, bool ALIGN_EPI = false, bool SP2 = false>
; __device__ __forceinline__ void gemm_phase(PG8_LAS unsigned char* lds, const Gemm g, const Sched& S, const Epi& E, volatile PG8_LAS unsigned* sw = nullptr) {
;     ...
;     const int tid = tid_, wid = __builtin_amdgcn_readfirstlane(tid >> 6), lane = tid & 63, wr = wid >> 2, wc = wid & 3, fr = lane & 15, fq = lane >> 4;
;     const int K = g.K, nt = K / BK;
;     unsigned voffA[2], voffB[2];
; #pragma unroll
;     for (int i = 0; i < 2; ++i) { int R, C; stage_rc(tid * 16 + i * 8192, R, C); const int Rb = Epi::PERM ? ((R & ~31) + perm32(R & 31)) : R;
;         const int Ra = Epi::PERMA ? ((R & 64) + 4 * (R & 15) + ((R >> 4) & 3)) : R;
;         voffA[i] = (unsigned)(Ra * BK + C) * 2u; voffB[i] = (unsigned)(Rb * BK + C) * 2u; }
;     const size_t kstep = (size_t)(BM * BK * 2);
;     const size_t hstep = (size_t)HALF * BK * 2;
;     const size_t tstep = (size_t)K * BM * 2;
;     const unsigned ldsw = (unsigned)wid * 1024u;
;     const int aoff = lds_byte(wr * 64 + fr, fq * 8), boff = lds_byte(wc * 32 + fr, fq * 8);
;     ...
;     Unit cur, nxt; int ui = 0;
;     if (!S.next(0, cur)) return;
;     if constexpr (Epi::PREFETCH) E.prefetch(cur, 0, wid, lane);
;     f32x4 acc[2][2][4][2];
; #pragma unroll
;     for (int a = 0; a < 2; ++a)
; #pragma unroll
;         for (int b = 0; b < 2; ++b)
; #pragma unroll
;             for (int m = 0; m < 4; ++m)
; #pragma unroll
;                 for (int n = 0; n < 2; ++n) acc[a][b][m][n] = (f32x4){0.f, 0.f, 0.f, 0.f};
;     bf16x8 At[4][2], B0[2][2], B1[2][2];
;     const char* cA = (const char*)g.A + (size_t)cur.pm * tstep; const char* cB = (const char*)g.Bt + (size_t)cur.pn * tstep;
;     S.a_ready(cur);
;     if constexpr (SP2) {
;         PG8_STAGE(PG8_SB(0, 0), cB, voffB); PG8_STAGE(PG8_SB(0, 1), cB + hstep, voffB); PG8_STAGE(PG8_SA(0, 0), cA, voffA); PG8_STAGE(PG8_SA(0, 1), cA + hstep, voffA);
;         if (wr == 1) PG8_BAR;
;         PG8_WAIT_V(2); PG8_BAR;
;         PG8_STAGE(PG8_SB(1, 0), cB + kstep, voffB); PG8_STAGE(PG8_SA(1, 0), cA + kstep, voffA); PG8_STAGE(PG8_SB(1, 1), cB + hstep + kstep, voffB);
;         PG8_WAIT_V(6); PG8_BAR;
;     } else {
;         PG8_STAGE(PG8_SB(0, 0), cB, voffB); PG8_STAGE(PG8_SA(0, 0), cA, voffA); PG8_STAGE(PG8_SB(0, 1), cB + hstep, voffB); PG8_STAGE(PG8_SA(0, 1), cA + hstep, voffA);
.LBB0_153:
	v_writelane_b32 v250, s70, 40
	s_nop 1
	v_writelane_b32 v250, s71, 41
	v_writelane_b32 v250, s68, 42
	s_nop 1
	v_writelane_b32 v250, s69, 43
	s_or_b64 exec, exec, s[0:1]
	s_and_saveexec_b64 s[4:5], s[80:81]
	v_mov_b32_e32 v1, 0x18800
	global_load_dword v2, v1, s[60:61] sc1
	s_waitcnt vmcnt(0)
	v_readfirstlane_b32 s100, v2
	s_or_b64 exec, exec, s[4:5]
	v_readlane_b32 s3, v250, 10
	s_mul_i32 s0, s3, 0x7000000
	s_add_u32 s0, s60, s0
	s_addc_u32 s1, s61, 0
	s_add_u32 s16, s0, 0x2800000
	s_addc_u32 s17, s1, 0
	s_ashr_i32 s97, s2, 3
	s_and_b32 s18, s2, 1
	s_ashr_i32 s62, s83, 3
	s_add_u32 s91, s60, 0x100000
	s_addc_u32 s92, s61, 0
	s_add_u32 s24, s0, 0x3800000
	s_addc_u32 s25, s1, 0
	s_lshl_b32 s60, s18, 4
	s_lshl_b32 s61, s3, 13
	v_mov_b32_e32 v2, v0
	s_waitcnt lgkmcnt(0)
	s_barrier
	s_cmpk_lt_i32 s97, 0x80
	s_nop 0
	v_readfirstlane_b32 s6, v2
	s_cbranch_scc0 .LBB0_173
	v_lshlrev_b32_e32 v1, 4, v2
	v_add_u32_e32 v4, 0x2000, v1
	v_ashrrev_i32_e32 v3, 31, v4
	v_lshrrev_b32_e32 v3, 22, v3
	v_add_u32_e32 v3, v4, v3
	v_ashrrev_i32_e32 v3, 10, v3
	v_mul_i32_i24_e32 v5, 0x400, v3
	v_sub_u32_e32 v4, v4, v5
	v_lshrrev_b32_e32 v5, 4, v4
	v_bitop3_b32 v5, v5, v4, 32 bitop3:0x6c
	v_ashrrev_i32_e32 v4, 31, v5
	v_lshrrev_b32_e32 v4, 26, v4
	v_add_u32_e32 v6, v5, v4
	v_lshlrev_b32_e32 v7, 3, v3
	v_ashrrev_i32_e32 v4, 6, v6
	v_and_b32_e32 v7, -16, v7
	v_add_u32_e32 v7, v4, v7
	v_and_b32_e32 v8, 3, v4
	s_mov_b32 s8, 0x1ffffe0
	v_lshrrev_b32_e32 v9, 2, v7
	v_lshlrev_b32_e32 v10, 1, v7
	v_and_or_b32 v8, v7, s8, v8
	v_and_b32_e32 v9, 4, v9
	v_and_b32_e32 v10, 24, v10
	v_and_b32_e32 v6, 0xc0, v6
	v_or3_b32 v8, v8, v9, v10
	v_sub_u32_e32 v5, v5, v6
	v_mov_b32_e32 v10, 1
	v_lshlrev_b32_e32 v9, 5, v3
	v_ashrrev_i16_sdwa v5, v10, sext(v5) dst_sel:DWORD dst_unused:UNUSED_PAD src0_sel:DWORD src1_sel:BYTE_0
	v_and_b32_e32 v9, 32, v9
	v_bfe_i32 v5, v5, 0, 16
	s_ashr_i32 s0, s97, 31
	v_add_lshl_u32 v6, v9, v5, 1
	s_lshr_b32 s0, s0, 26
	v_lshl_add_u32 v130, v8, 7, v6
	v_lshl_add_u32 v132, v7, 7, v6
	v_bfe_i32 v6, v2, 27, 1
	s_add_i32 s0, s97, s0
	v_lshrrev_b32_e32 v6, 22, v6
	s_ashr_i32 s1, s0, 6
	s_andn2_b32 s0, s0, 63
	v_add_u32_e32 v6, v1, v6
	s_sub_i32 s0, s97, s0
	s_lshl_b32 s1, s1, 3
	v_and_b32_e32 v6, 0xfffffc00, v6
	s_add_i32 s1, s1, s60
	s_and_b32 s2, s0, 7
	v_sub_u32_e32 v1, v1, v6
	s_or_b32 s46, s1, s2
	s_ashr_i32 s2, s0, 3
	v_lshrrev_b32_e32 v6, 4, v1
	v_ashrrev_i32_e32 v7, 31, v2
	s_ashr_i32 s47, s46, 31
	s_ashr_i32 s3, s2, 31
	v_bitop3_b32 v1, v6, v1, 32 bitop3:0x6c
	v_lshrrev_b32_e32 v7, 26, v7
	s_lshl_b64 s[0:1], s[46:47], 19
	s_lshl_b64 s[4:5], s[2:3], 19
	v_ashrrev_i32_e32 v6, 31, v1
	v_add_u32_e32 v7, v2, v7
	s_add_u32 s50, s14, s4
	v_lshrrev_b32_e32 v6, 26, v6
	v_ashrrev_i32_e32 v7, 6, v7
	s_addc_u32 s51, s15, s5
	v_add_u32_e32 v8, v1, v6
	v_lshlrev_b32_e32 v9, 3, v7
	s_add_u32 s48, s16, s0
	v_ashrrev_i32_e32 v6, 6, v8
	v_and_b32_e32 v9, -16, v9
	s_addc_u32 s49, s17, s1
	s_ashr_i32 s3, s6, 6
	v_add_u32_e32 v9, v6, v9
	s_ashr_i32 s7, s6, 8
	s_lshl_b32 s19, s3, 10
	v_and_b32_e32 v11, 3, v6
	v_lshrrev_b32_e32 v12, 2, v9
	v_lshlrev_b32_e32 v13, 1, v9
	v_and_b32_e32 v8, 0xc0, v8
	s_add_u32 s0, s48, 0x4000
	v_and_or_b32 v11, v9, s8, v11
	v_and_b32_e32 v12, 4, v12
	v_and_b32_e32 v13, 24, v13
	v_sub_u32_e32 v1, v1, v8
	s_addc_u32 s1, s49, 0
	v_or3_b32 v11, v11, v12, v13
	v_lshlrev_b32_e32 v12, 5, v7
	v_ashrrev_i16_sdwa v1, v10, sext(v1) dst_sel:DWORD dst_unused:UNUSED_PAD src0_sel:DWORD src1_sel:BYTE_0
	s_add_u32 s4, s50, 0x4000
	v_and_b32_e32 v12, 32, v12
	v_bfe_i32 v8, v1, 0, 16
	s_addc_u32 s5, s51, 0
	v_add_lshl_u32 v1, v12, v8, 1
	s_add_i32 s20, s19, 0
	v_lshl_add_u32 v134, v11, 7, v1
	s_add_i32 m0, s20, 0x10000
	v_lshl_add_u32 v136, v9, 7, v1
	global_load_lds_dwordx4 v134, s[50:51]
	s_add_i32 m0, s20, 0x12000
	s_add_i32 s21, s20, 0x2000
	global_load_lds_dwordx4 v130, s[50:51]
	s_add_i32 m0, s20, 0x14000
	s_add_i32 s22, s20, 0x4000
	global_load_lds_dwordx4 v134, s[4:5]
	s_add_i32 m0, s20, 0x16000
	s_add_i32 s23, s20, 0x6000
	global_load_lds_dwordx4 v130, s[4:5]
	s_mov_b32 m0, s20
	v_mov_b32_e32 v135, 0
	global_load_lds_dwordx4 v136, s[48:49]
	s_mov_b32 m0, s21
	s_cmp_eq_u32 s7, 1
	global_load_lds_dwordx4 v132, s[48:49]
	s_mov_b32 m0, s22
	v_mov_b32_e32 v131, v135
	global_load_lds_dwordx4 v136, s[0:1]
	s_mov_b32 m0, s23
	v_mov_b32_e32 v137, v135
	global_load_lds_dwordx4 v132, s[0:1]
	s_cselect_b64 s[4:5], -1, 0
	s_cmp_lg_u32 s7, 1
	v_mov_b32_e32 v133, v135
	s_cbranch_scc1 .LBB0_156
	s_barrier

; __device__ __forceinline__ unsigned xb_ld(unsigned* p)              { return __hip_atomic_load(p, __ATOMIC_RELAXED, __HIP_MEMORY_SCOPE_AGENT); }
; __device__ __forceinline__ unsigned xb_add(unsigned* p, unsigned v) { return __hip_atomic_fetch_add(p, v, __ATOMIC_RELAXED, __HIP_MEMORY_SCOPE_AGENT); }
; #define XB_SPIN(cond, bar) do { unsigned _sp = 0; while (cond) { __builtin_amdgcn_s_sleep(1); \
;     if ((++_sp & 255u) == 0u) { if (xb_ld(&(bar)[XB_TMO])) break; if (_sp > XB_SPIN_CAP) { atomicAdd(&(bar)[XB_TMO], 1u); break; } } } } while (0)
; __device__ __forceinline__ void xcd_barrier(const XcdBarrier& b) {
;     asm volatile("s_waitcnt vmcnt(0)" ::: "memory");
;     __syncthreads();
;     if (threadIdx.x == 0) {
;         unsigned* bar = b.bar;
;         __builtin_amdgcn_s_waitcnt(0);
;         unsigned nloc = b.st[0], nx = b.st[1];
;         if (nloc == 0u) { xcd_barrier_complete(bar, b.x, b.gsize, nloc, nx); b.st[0] = nloc; b.st[1] = nx; }
;         const unsigned old = xb_add(&bar[XB_XSUB(b.x)], 1u);
;         const unsigned gen = old / nloc;
;         if (old + 1u == (gen + 1u) * nloc) {
;             __builtin_amdgcn_fence(__ATOMIC_RELEASE, "agent");
;             asm volatile("s_waitcnt vmcnt(0)" ::: "memory");
;             const unsigned og = xb_add(&bar[XB_TOP], 1u);
;             const unsigned tg = og / nx;
;             if (og + 1u == (tg + 1u) * nx) xb_add(&bar[XB_TOPGEN], 1u);
;             else XB_SPIN(xb_ld(&bar[XB_TOPGEN]) == tg, bar);
;             __builtin_amdgcn_fence(__ATOMIC_ACQUIRE, "agent");
;             xb_add(&bar[XB_XGEN(b.x)], 1u);
;             asm volatile("s_waitcnt vmcnt(0)" ::: "memory");
;         } else {
;             XB_SPIN(xb_ld(&bar[XB_XGEN(b.x)]) == gen, bar);
;             __builtin_amdgcn_fence(__ATOMIC_ACQUIRE, "agent");
;             asm volatile("s_waitcnt vmcnt(0)" ::: "memory");
;         }
;     }
;     __syncthreads();
; }
.LBB0_457:
	s_waitcnt vmcnt(0)
	s_barrier
	s_and_saveexec_b64 s[0:1], s[90:91]
	s_xor_b64 s[0:1], exec, s[0:1]
	s_cbranch_execz .LBB0_510
	s_cmp_lg_u32 s100, 0
	s_cbranch_scc1 .Lq4_slow
	v_readlane_b32 s4, v250, 14
	v_readlane_b32 s5, v250, 15
	s_and_b32 s6, s101, 7
	s_lshl_b32 s6, s6, 3
	s_bfe_u32 s7, s101, 0x30003
	s_or_b32 s6, s6, s7
	s_lshl_b32 s6, s6, 7
	s_add_i32 s6, s6, 0x19000
	v_mov_b32_e32 v1, s6
	v_mov_b32_e32 v2, 1
	s_mov_b32 s7, 0
	s_nop 4
	global_atomic_add v1, v2, s[4:5]
.Lq4_spin:
	global_load_dword v3, v1, s[4:5] sc1
	s_waitcnt vmcnt(0)
	v_cmp_gt_u32_e32 vcc, 4, v3
	s_cbranch_vccz .Lq4_ok
	s_sleep 1
	s_add_i32 s7, s7, 1
	s_cmp_lt_u32 s7, 0x8000
	s_cbranch_scc1 .Lq4_spin
.Lq4_ok:
	buffer_inv sc1
	s_waitcnt vmcnt(0)
	s_branch .LBB0_510
.Lq4_slow:
	s_add_i32 s2, 0, 0x26170
	v_mov_b32_e32 v1, s2
	s_waitcnt vmcnt(0) expcnt(0) lgkmcnt(0)
	ds_read_b32 v3, v1
	s_add_i32 s2, 0, 0x26174
	v_mov_b32_e32 v1, s2
	ds_read_b32 v1, v1
	s_waitcnt lgkmcnt(1)
	v_cmp_ne_u32_e32 vcc, 0, v3
	s_cbranch_vccnz .LBB0_473
	s_add_u32 s2, s34, 0x1000
	s_addc_u32 s3, s35, 0
	s_add_u32 s4, s34, 0x1100
	s_addc_u32 s5, s35, 0
	s_add_u32 s6, s34, 0x1200
	s_addc_u32 s7, s35, 0
	s_add_u32 s8, s34, 0x1300
	s_addc_u32 s9, s35, 0
	s_mov_b32 s11, 1
	v_mov_b32_e32 v17, 0
	s_branch .LBB0_461

; __global__ void __launch_bounds__(NWAVES * 64, 2) fwd(Args a) {
;     ...
;         for (int idx = (xh * cph + gk) * 512 + tid; idx < 2 * GPANELS * (FF / 8); idx += gsz * 512) {
;             const int br = idx / (FF / 8), f = 8 * (idx % (FF / 8)), gcol = (f >> 7) * 256 + (f & 127);
;             const int pm = pm0 + (br >> 1), last = br & 1, row = pm * 256 + (last ? 255 : 0);
;             const int b = batch_of_row(row), t = row < NPR ? (row & 2047) : ((row - NPR) & 8191), T = b < 8 ? 2048 : 8192;
.LBB0_615:
	s_or_b64 exec, exec, s[0:1]
	s_waitcnt lgkmcnt(0)
	v_mov_b32_e32 v1, v0
	s_barrier
	s_and_b32 s0, s101, 1
	s_lshl_b32 s0, s0, 4
	s_bfe_u32 s1, s101, 0x30003
	s_add_i32 s0, s0, s1
	s_bfe_u32 s1, s101, 0x10007
	s_lshl_b32 s1, s1, 3
	s_add_i32 s0, s0, s1
	s_lshl_b32 s0, s0, 1
	s_bfe_u32 s1, s101, 0x10006
	s_or_b32 s0, s0, s1
	s_mulk_i32 s0, 0x160
	s_movk_i32 s1, 0x160
	v_cmp_gt_u32_e32 vcc, s1, v1
	v_add_u32_e32 v1, s0, v1
	s_and_saveexec_b64 s[4:5], vcc
	s_cbranch_execz .LBB0_638
	s_add_u32 s6, s62, 0x1a05800
	s_addc_u32 s7, s63, 0
	s_add_u32 s8, s62, 0x1a0b000
	s_addc_u32 s9, s63, 0
	s_lshl_b32 s11, s60, 9
	v_lshlrev_b32_e32 v104, 3, v1
	s_lshl_b32 s13, s60, 12
	v_lshlrev_b32_e32 v105, 4, v1
	s_lshl_b32 s14, s60, 13
	s_mov_b64 s[20:21], 0
	s_mov_b32 s15, 0x2e8ba2e9
	s_mov_b32 s30, 0x16000
	s_mov_b64 s[24:25], 0xb000
	s_mov_b64 s[26:27], 0x10800
	s_mov_b64 s[28:29], 0x5800
	s_movk_i32 s31, 0xff00
	v_mov_b32_e32 v106, 0xff
	s_movk_i32 s33, 0x4000
	v_mov_b32_e32 v107, 0x1fff
	v_mov_b32_e32 v108, 0x7ff
	s_movk_i32 s36, 0x7fff
	s_mov_b32 s37, 0xffff0000
	v_mov_b32_e32 v99, 0
	s_movk_i32 s38, 0x57ff
	s_branch .LBB0_618

; __device__ __forceinline__ unsigned xb_ld(unsigned* p)              { return __hip_atomic_load(p, __ATOMIC_RELAXED, __HIP_MEMORY_SCOPE_AGENT); }
; __device__ __forceinline__ unsigned xb_add(unsigned* p, unsigned v) { return __hip_atomic_fetch_add(p, v, __ATOMIC_RELAXED, __HIP_MEMORY_SCOPE_AGENT); }
; #define XB_SPIN(cond, bar) do { unsigned _sp = 0; while (cond) { __builtin_amdgcn_s_sleep(1); \
;     if ((++_sp & 255u) == 0u) { if (xb_ld(&(bar)[XB_TMO])) break; if (_sp > XB_SPIN_CAP) { atomicAdd(&(bar)[XB_TMO], 1u); break; } } } } while (0)
; __device__ __forceinline__ void xcd_barrier(const XcdBarrier& b) {
;     asm volatile("s_waitcnt vmcnt(0)" ::: "memory");
;     __syncthreads();
;     if (threadIdx.x == 0) {
;         unsigned* bar = b.bar;
;         __builtin_amdgcn_s_waitcnt(0);
;         unsigned nloc = b.st[0], nx = b.st[1];
;         if (nloc == 0u) { xcd_barrier_complete(bar, b.x, b.gsize, nloc, nx); b.st[0] = nloc; b.st[1] = nx; }
;         const unsigned old = xb_add(&bar[XB_XSUB(b.x)], 1u);
;         const unsigned gen = old / nloc;
;         if (old + 1u == (gen + 1u) * nloc) {
;             __builtin_amdgcn_fence(__ATOMIC_RELEASE, "agent");
;             asm volatile("s_waitcnt vmcnt(0)" ::: "memory");
;             const unsigned og = xb_add(&bar[XB_TOP], 1u);
;             const unsigned tg = og / nx;
;             if (og + 1u == (tg + 1u) * nx) xb_add(&bar[XB_TOPGEN], 1u);
;             else XB_SPIN(xb_ld(&bar[XB_TOPGEN]) == tg, bar);
;             __builtin_amdgcn_fence(__ATOMIC_ACQUIRE, "agent");
;             xb_add(&bar[XB_XGEN(b.x)], 1u);
;             asm volatile("s_waitcnt vmcnt(0)" ::: "memory");
;         } else {
;             XB_SPIN(xb_ld(&bar[XB_XGEN(b.x)]) == gen, bar);
;             __builtin_amdgcn_fence(__ATOMIC_ACQUIRE, "agent");
;             asm volatile("s_waitcnt vmcnt(0)" ::: "memory");
;         }
;     }
;     __syncthreads();
; }
.LBB0_638:
	s_or_b64 exec, exec, s[4:5]
	s_waitcnt vmcnt(0)
	s_barrier
	s_and_saveexec_b64 s[0:1], s[90:91]
	v_readlane_b32 s62, v250, 42
	v_readlane_b32 s64, v250, 40
	v_readlane_b32 s63, v250, 43
	v_readlane_b32 s65, v250, 41
	s_cbranch_execz .LBB0_690
	s_cmp_lg_u32 s100, 0
	s_cbranch_scc1 .Lq6_slow
	v_readlane_b32 s4, v250, 14
	v_readlane_b32 s5, v250, 15
	s_and_b32 s6, s101, 7
	s_lshl_b32 s6, s6, 3
	s_bfe_u32 s7, s101, 0x30003
	s_or_b32 s6, s6, s7
	s_lshl_b32 s6, s6, 7
	s_add_i32 s6, s6, 0x1b000
	v_mov_b32_e32 v1, s6
	v_mov_b32_e32 v2, 1
	s_mov_b32 s7, 0
	s_nop 4
	global_atomic_add v1, v2, s[4:5]
